# ph12 tile epilogue: -log2(e) folded into the row rinv and packed +1 (two VALU fewer per element pair), all f32
# baseline (speedup 1.0000x reference)
; __device__ __forceinline__ float bf_lo(unsigned w) { return __uint_as_float(w << 16); }
; __device__ __forceinline__ float bf_hi(unsigned w) { return __uint_as_float(w & 0xffff0000u); }
; __device__ __forceinline__ float sigmoidf_(float x) { return __builtin_amdgcn_rcpf(1.0f + __expf(-x)); }
; __device__ __forceinline__ float rinv_of(float ssq) { return rsqrtf(ssq * (1.0f / 1024.0f) + EPS); }
; __device__ __forceinline__ u32x4 pack8(const f32x4 a, const f32x4 b) { u32x4 w; w.x = cvt_pk_bf16(a[0], a[1]); w.y = cvt_pk_bf16(a[2], a[3]); w.z = cvt_pk_bf16(b[0], b[1]); w.w = cvt_pk_bf16(b[2], b[3]); return w; }
;     __device__ __forceinline__ void operator()(const AccT& acc, const pg8::Unit& u, int wr, int wc, int fr, int fq) const {
;     ...
;                 for (int mm = 0; mm < 2; ++mm) { const int r = EPI_ROW(u, ai, 2 * mp + mm); rs[mm] = ssq_in[r];
; #pragma unroll
;                     for (int bj = 0; bj < 2; ++bj) { const int c = EPI_COL(u, bj); const float* hp = h + (size_t)r * D + c; hv[mm][bj][0] = *(const f32x4*)hp; hv[mm][bj][1] = *(const f32x4*)(hp + 4); pw[mm][bj] = *(const u32x4*)(pp + (size_t)r * D + c); } }
; #pragma unroll
;                 for (int mm = 0; mm < 2; ++mm) { const int m = 2 * mp + mm, r = EPI_ROW(u, ai, m); float s = 0.f; const float ri = rinv_of(rs[mm]);
; #pragma unroll
;                     for (int bj = 0; bj < 2; ++bj) { const int c = EPI_COL(u, bj); float* hp = h + (size_t)r * D + c; const u32x4 p4 = pw[mm][bj];
;                         const f32x4 a0 = acc[ai][bj][m][0] * ri, a1 = acc[ai][bj][m][1] * ri; f32x4 v0 = hv[mm][bj][0], v1 = hv[mm][bj][1];
;                         v0[0] += mul * sigmoidf_(a0[0]) * bf_lo(p4.x); v0[1] += mul * sigmoidf_(a0[1]) * bf_hi(p4.x); v0[2] += mul * sigmoidf_(a0[2]) * bf_lo(p4.y); v0[3] += mul * sigmoidf_(a0[3]) * bf_hi(p4.y);
;                         v1[0] += mul * sigmoidf_(a1[0]) * bf_lo(p4.z); v1[1] += mul * sigmoidf_(a1[1]) * bf_hi(p4.z); v1[2] += mul * sigmoidf_(a1[2]) * bf_lo(p4.w); v1[3] += mul * sigmoidf_(a1[3]) * bf_hi(p4.w);
;                         *(f32x4*)hp = v0; *(f32x4*)(hp + 4) = v1;
;                         if (hb) *(u32x4*)(hb + (size_t)r * D + c) = pack8(v0, v1);
;                         s += sq8(v0, v1); }
;                     ssq_commit(s, ssq, r, fq); }
.LBB0_2621:
	s_lshl_b32 s12, s36, 8
	s_lshl_b32 s13, s42, 6
	s_add_i32 s12, s12, s13
	v_add_u32_e32 v241, s12, v180
	s_lshl_b32 s12, s34, 8
	s_lshl_b32 s13, s47, 5
	s_add_i32 s12, s12, s13
	v_lshl_add_u32 v242, v181, 3, s12
	v_lshlrev_b32_e32 v243, 12, v241
	v_lshl_add_u32 v243, v242, 2, v243
	v_lshlrev_b32_e32 v226, 2, v241
	v_mov_b32_e32 v225, 0x358637bd
	v_mbcnt_lo_u32_b32 v224, -1, 0
	v_mbcnt_hi_u32_b32 v224, -1, v224
	v_lshlrev_b32_e32 v224, 2, v224
	v_cmp_eq_u32_e64 s[98:99], 0, v181
	v_mov_b32_e32 v232, v243
	v_lshrrev_b32_e32 v233, 1, v232
	global_load_dword v176, v226, s[14:15]
	global_load_dwordx4 v[128:131], v232, s[52:53]
	global_load_dwordx4 v[132:135], v232, s[52:53] offset:16
	global_load_dwordx4 v[136:139], v232, s[52:53] offset:512
	global_load_dwordx4 v[140:143], v232, s[52:53] offset:528
	global_load_dwordx4 v[144:147], v233, s[72:73]
	global_load_dwordx4 v[148:151], v233, s[72:73] offset:256
	v_add_u32_e32 v232, 0x10000, v243
	v_lshrrev_b32_e32 v233, 1, v232
	global_load_dword v177, v226, s[14:15] offset:64
	global_load_dwordx4 v[152:155], v232, s[52:53]
	global_load_dwordx4 v[156:159], v232, s[52:53] offset:16
	global_load_dwordx4 v[160:163], v232, s[52:53] offset:512
	global_load_dwordx4 v[164:167], v232, s[52:53] offset:528
	global_load_dwordx4 v[168:171], v233, s[72:73]
	global_load_dwordx4 v[172:175], v233, s[72:73] offset:256
	v_add_u32_e32 v232, 0x20000, v243
	v_lshrrev_b32_e32 v233, 1, v232
	global_load_dword v227, v226, s[14:15] offset:128
	global_load_dwordx4 v[178:181], v232, s[52:53]
	global_load_dwordx4 v[182:185], v232, s[52:53] offset:16
	global_load_dwordx4 v[186:189], v232, s[52:53] offset:512
	global_load_dwordx4 v[190:193], v232, s[52:53] offset:528
	global_load_dwordx4 v[212:215], v233, s[72:73]
	global_load_dwordx4 v[216:219], v233, s[72:73] offset:256
	v_add_u32_e32 v232, 0x30000, v243
	v_lshrrev_b32_e32 v233, 1, v232
	global_load_dword v228, v226, s[14:15] offset:192
	global_load_dwordx4 v[194:197], v232, s[52:53]
	global_load_dwordx4 v[198:201], v232, s[52:53] offset:16
	global_load_dwordx4 v[202:205], v232, s[52:53] offset:512
	global_load_dwordx4 v[206:209], v232, s[52:53] offset:528
	global_load_dwordx4 v[220:223], v233, s[72:73]
	global_load_dwordx4 v[244:247], v233, s[72:73] offset:256
	s_waitcnt vmcnt(21)
	v_fmamk_f32 v230, v176, 0x3a800000, v225
	v_rsq_f32_e32 v230, v230
	v_mov_b32_e32 v229, 0
	v_mul_f32_e32 v230, 0xbfb8aa3b, v230
	v_pk_mul_f32 v[236:237], v[124:125], v[230:231] op_sel_hi:[1,0]
	v_pk_mul_f32 v[238:239], v[126:127], v[230:231] op_sel_hi:[1,0]
	v_exp_f32_e32 v236, v236
	v_exp_f32_e32 v237, v237
	v_exp_f32_e32 v238, v238
	v_exp_f32_e32 v239, v239
	v_pk_add_f32 v[236:237], v[236:237], 1.0 op_sel_hi:[1,0]
	v_pk_add_f32 v[238:239], v[238:239], 1.0 op_sel_hi:[1,0]
	v_rcp_f32_e32 v236, v236
	v_rcp_f32_e32 v237, v237
	v_rcp_f32_e32 v238, v238
	v_rcp_f32_e32 v239, v239
	v_lshlrev_b32_e32 v232, 16, v144
	v_and_b32_e32 v233, 0xffff0000, v144
	v_lshlrev_b32_e32 v234, 16, v145
	v_and_b32_e32 v235, 0xffff0000, v145
	v_pk_fma_f32 v[124:125], v[236:237], v[232:233], v[128:129]
	v_pk_fma_f32 v[126:127], v[238:239], v[234:235], v[130:131]
	v_pk_mul_f32 v[236:237], v[124:125], v[124:125]
	v_pk_mul_f32 v[238:239], v[126:127], v[126:127]
	v_add_f32_e32 v229, v229, v236
	v_add_f32_e32 v229, v229, v237
	v_add_f32_e32 v229, v229, v238
	v_add_f32_e32 v229, v229, v239
	v_pk_mul_f32 v[236:237], v[120:121], v[230:231] op_sel_hi:[1,0]
	v_pk_mul_f32 v[238:239], v[122:123], v[230:231] op_sel_hi:[1,0]
	v_exp_f32_e32 v236, v236
	v_exp_f32_e32 v237, v237
	v_exp_f32_e32 v238, v238
	v_exp_f32_e32 v239, v239
	v_pk_add_f32 v[236:237], v[236:237], 1.0 op_sel_hi:[1,0]
	v_pk_add_f32 v[238:239], v[238:239], 1.0 op_sel_hi:[1,0]
	v_rcp_f32_e32 v236, v236
	v_rcp_f32_e32 v237, v237
	v_rcp_f32_e32 v238, v238
	v_rcp_f32_e32 v239, v239
	v_lshlrev_b32_e32 v232, 16, v146
	v_and_b32_e32 v233, 0xffff0000, v146
	v_lshlrev_b32_e32 v234, 16, v147
	v_and_b32_e32 v235, 0xffff0000, v147
	v_pk_fma_f32 v[120:121], v[236:237], v[232:233], v[132:133]
	v_pk_fma_f32 v[122:123], v[238:239], v[234:235], v[134:135]
	v_pk_mul_f32 v[236:237], v[120:121], v[120:121]
	v_pk_mul_f32 v[238:239], v[122:123], v[122:123]
	v_add_f32_e32 v229, v229, v236
	v_add_f32_e32 v229, v229, v237
	v_add_f32_e32 v229, v229, v238
	v_add_f32_e32 v229, v229, v239
	v_pk_mul_f32 v[236:237], v[116:117], v[230:231] op_sel_hi:[1,0]
	v_pk_mul_f32 v[238:239], v[118:119], v[230:231] op_sel_hi:[1,0]
	v_exp_f32_e32 v236, v236
	v_exp_f32_e32 v237, v237
	v_exp_f32_e32 v238, v238
	v_exp_f32_e32 v239, v239
	v_pk_add_f32 v[236:237], v[236:237], 1.0 op_sel_hi:[1,0]
	v_pk_add_f32 v[238:239], v[238:239], 1.0 op_sel_hi:[1,0]
	v_rcp_f32_e32 v236, v236
	v_rcp_f32_e32 v237, v237
	v_rcp_f32_e32 v238, v238
	v_rcp_f32_e32 v239, v239
	v_lshlrev_b32_e32 v232, 16, v148
	v_and_b32_e32 v233, 0xffff0000, v148
	v_lshlrev_b32_e32 v234, 16, v149
	v_and_b32_e32 v235, 0xffff0000, v149
	v_pk_fma_f32 v[116:117], v[236:237], v[232:233], v[136:137]
	v_pk_fma_f32 v[118:119], v[238:239], v[234:235], v[138:139]
	v_pk_mul_f32 v[236:237], v[116:117], v[116:117]
	v_pk_mul_f32 v[238:239], v[118:119], v[118:119]
	v_add_f32_e32 v229, v229, v236
	v_add_f32_e32 v229, v229, v237
	v_add_f32_e32 v229, v229, v238
	v_add_f32_e32 v229, v229, v239
	v_pk_mul_f32 v[236:237], v[112:113], v[230:231] op_sel_hi:[1,0]
	v_pk_mul_f32 v[238:239], v[114:115], v[230:231] op_sel_hi:[1,0]
	v_exp_f32_e32 v236, v236
	v_exp_f32_e32 v237, v237
	v_exp_f32_e32 v238, v238
	v_exp_f32_e32 v239, v239
	v_pk_add_f32 v[236:237], v[236:237], 1.0 op_sel_hi:[1,0]
	v_pk_add_f32 v[238:239], v[238:239], 1.0 op_sel_hi:[1,0]
	v_rcp_f32_e32 v236, v236
	v_rcp_f32_e32 v237, v237
	v_rcp_f32_e32 v238, v238
	v_rcp_f32_e32 v239, v239
	v_lshlrev_b32_e32 v232, 16, v150
	v_and_b32_e32 v233, 0xffff0000, v150
	v_lshlrev_b32_e32 v234, 16, v151
	v_and_b32_e32 v235, 0xffff0000, v151
	v_pk_fma_f32 v[112:113], v[236:237], v[232:233], v[140:141]
	v_pk_fma_f32 v[114:115], v[238:239], v[234:235], v[142:143]
	v_pk_mul_f32 v[236:237], v[112:113], v[112:113]
	v_pk_mul_f32 v[238:239], v[114:115], v[114:115]
	v_add_f32_e32 v229, v229, v236
	v_add_f32_e32 v229, v229, v237
	v_add_f32_e32 v229, v229, v238
	v_add_f32_e32 v229, v229, v239
	v_xor_b32_e32 v232, 64, v224
	ds_bpermute_b32 v233, v232, v229
	s_waitcnt lgkmcnt(0)
; __device__ __forceinline__ float bf_lo(unsigned w) { return __uint_as_float(w << 16); }
; __device__ __forceinline__ float bf_hi(unsigned w) { return __uint_as_float(w & 0xffff0000u); }
; __device__ __forceinline__ float sigmoidf_(float x) { return __builtin_amdgcn_rcpf(1.0f + __expf(-x)); }
; __device__ __forceinline__ float rinv_of(float ssq) { return rsqrtf(ssq * (1.0f / 1024.0f) + EPS); }
; __device__ __forceinline__ u32x4 pack8(const f32x4 a, const f32x4 b) { u32x4 w; w.x = cvt_pk_bf16(a[0], a[1]); w.y = cvt_pk_bf16(a[2], a[3]); w.z = cvt_pk_bf16(b[0], b[1]); w.w = cvt_pk_bf16(b[2], b[3]); return w; }
; __device__ __forceinline__ float sq8(const f32x4 a, const f32x4 b) { return (a[0] * a[0] + a[1] * a[1]) + (a[2] * a[2] + a[3] * a[3]) + (b[0] * b[0] + b[1] * b[1]) + (b[2] * b[2] + b[3] * b[3]); }
; __device__ __forceinline__ void ssq_commit(float s, float* ssq, int r, int fq) { s += __shfl_xor(s, 16); s += __shfl_xor(s, 32); if (fq == 0) atomicAdd(ssq + r, s); }
;     __device__ __forceinline__ void operator()(const AccT& acc, const pg8::Unit& u, int wr, int wc, int fr, int fq) const {
;     ...
;                 for (int mm = 0; mm < 2; ++mm) { const int m = 2 * mp + mm, r = EPI_ROW(u, ai, m); float s = 0.f; const float ri = rinv_of(rs[mm]);
; #pragma unroll
;                     for (int bj = 0; bj < 2; ++bj) { const int c = EPI_COL(u, bj); float* hp = h + (size_t)r * D + c; const u32x4 p4 = pw[mm][bj];
;                         const f32x4 a0 = acc[ai][bj][m][0] * ri, a1 = acc[ai][bj][m][1] * ri; f32x4 v0 = hv[mm][bj][0], v1 = hv[mm][bj][1];
;                         v0[0] += mul * sigmoidf_(a0[0]) * bf_lo(p4.x); v0[1] += mul * sigmoidf_(a0[1]) * bf_hi(p4.x); v0[2] += mul * sigmoidf_(a0[2]) * bf_lo(p4.y); v0[3] += mul * sigmoidf_(a0[3]) * bf_hi(p4.y);
;                         v1[0] += mul * sigmoidf_(a1[0]) * bf_lo(p4.z); v1[1] += mul * sigmoidf_(a1[1]) * bf_hi(p4.z); v1[2] += mul * sigmoidf_(a1[2]) * bf_lo(p4.w); v1[3] += mul * sigmoidf_(a1[3]) * bf_hi(p4.w);
;                         *(f32x4*)hp = v0; *(f32x4*)(hp + 4) = v1;
;                         if (hb) *(u32x4*)(hb + (size_t)r * D + c) = pack8(v0, v1);
;                         s += sq8(v0, v1); }
;                     ssq_commit(s, ssq, r, fq); }
	v_add_f32_e32 v229, v229, v233
	v_xor_b32_e32 v232, 0x80, v224
	ds_bpermute_b32 v233, v232, v229
	s_waitcnt lgkmcnt(0)
	v_add_f32_e32 v229, v229, v233
	s_and_saveexec_b64 s[100:101], s[98:99]
	global_atomic_add_f32 v226, v229, s[16:17]
	s_mov_b64 exec, s[100:101]
	s_waitcnt vmcnt(15)
	v_fmamk_f32 v230, v177, 0x3a800000, v225
	v_rsq_f32_e32 v230, v230
	v_mov_b32_e32 v229, 0
	v_mul_f32_e32 v230, 0xbfb8aa3b, v230
	v_pk_mul_f32 v[236:237], v[108:109], v[230:231] op_sel_hi:[1,0]
	v_pk_mul_f32 v[238:239], v[110:111], v[230:231] op_sel_hi:[1,0]
	v_exp_f32_e32 v236, v236
	v_exp_f32_e32 v237, v237
	v_exp_f32_e32 v238, v238
	v_exp_f32_e32 v239, v239
	v_pk_add_f32 v[236:237], v[236:237], 1.0 op_sel_hi:[1,0]
	v_pk_add_f32 v[238:239], v[238:239], 1.0 op_sel_hi:[1,0]
	v_rcp_f32_e32 v236, v236
	v_rcp_f32_e32 v237, v237
	v_rcp_f32_e32 v238, v238
	v_rcp_f32_e32 v239, v239
	v_lshlrev_b32_e32 v232, 16, v168
	v_and_b32_e32 v233, 0xffff0000, v168
	v_lshlrev_b32_e32 v234, 16, v169
	v_and_b32_e32 v235, 0xffff0000, v169
	v_pk_fma_f32 v[108:109], v[236:237], v[232:233], v[152:153]
	v_pk_fma_f32 v[110:111], v[238:239], v[234:235], v[154:155]
	v_pk_mul_f32 v[236:237], v[108:109], v[108:109]
	v_pk_mul_f32 v[238:239], v[110:111], v[110:111]
	v_add_f32_e32 v229, v229, v236
	v_add_f32_e32 v229, v229, v237
	v_add_f32_e32 v229, v229, v238
	v_add_f32_e32 v229, v229, v239
	v_pk_mul_f32 v[236:237], v[104:105], v[230:231] op_sel_hi:[1,0]
	v_pk_mul_f32 v[238:239], v[106:107], v[230:231] op_sel_hi:[1,0]
	v_exp_f32_e32 v236, v236
	v_exp_f32_e32 v237, v237
	v_exp_f32_e32 v238, v238
	v_exp_f32_e32 v239, v239
	v_pk_add_f32 v[236:237], v[236:237], 1.0 op_sel_hi:[1,0]
	v_pk_add_f32 v[238:239], v[238:239], 1.0 op_sel_hi:[1,0]
	v_rcp_f32_e32 v236, v236
	v_rcp_f32_e32 v237, v237
	v_rcp_f32_e32 v238, v238
	v_rcp_f32_e32 v239, v239
	v_lshlrev_b32_e32 v232, 16, v170
	v_and_b32_e32 v233, 0xffff0000, v170
	v_lshlrev_b32_e32 v234, 16, v171
	v_and_b32_e32 v235, 0xffff0000, v171
	v_pk_fma_f32 v[104:105], v[236:237], v[232:233], v[156:157]
	v_pk_fma_f32 v[106:107], v[238:239], v[234:235], v[158:159]
	v_pk_mul_f32 v[236:237], v[104:105], v[104:105]
	v_pk_mul_f32 v[238:239], v[106:107], v[106:107]
	v_add_f32_e32 v229, v229, v236
	v_add_f32_e32 v229, v229, v237
	v_add_f32_e32 v229, v229, v238
	v_add_f32_e32 v229, v229, v239
	v_pk_mul_f32 v[236:237], v[100:101], v[230:231] op_sel_hi:[1,0]
	v_pk_mul_f32 v[238:239], v[102:103], v[230:231] op_sel_hi:[1,0]
	v_exp_f32_e32 v236, v236
	v_exp_f32_e32 v237, v237
	v_exp_f32_e32 v238, v238
	v_exp_f32_e32 v239, v239
	v_pk_add_f32 v[236:237], v[236:237], 1.0 op_sel_hi:[1,0]
	v_pk_add_f32 v[238:239], v[238:239], 1.0 op_sel_hi:[1,0]
	v_rcp_f32_e32 v236, v236
	v_rcp_f32_e32 v237, v237
	v_rcp_f32_e32 v238, v238
	v_rcp_f32_e32 v239, v239
	v_lshlrev_b32_e32 v232, 16, v172
	v_and_b32_e32 v233, 0xffff0000, v172
	v_lshlrev_b32_e32 v234, 16, v173
	v_and_b32_e32 v235, 0xffff0000, v173
	v_pk_fma_f32 v[100:101], v[236:237], v[232:233], v[160:161]
	v_pk_fma_f32 v[102:103], v[238:239], v[234:235], v[162:163]
	v_pk_mul_f32 v[236:237], v[100:101], v[100:101]
	v_pk_mul_f32 v[238:239], v[102:103], v[102:103]
	v_add_f32_e32 v229, v229, v236
	v_add_f32_e32 v229, v229, v237
	v_add_f32_e32 v229, v229, v238
	v_add_f32_e32 v229, v229, v239
	v_pk_mul_f32 v[236:237], v[96:97], v[230:231] op_sel_hi:[1,0]
	v_pk_mul_f32 v[238:239], v[98:99], v[230:231] op_sel_hi:[1,0]
	v_exp_f32_e32 v236, v236
	v_exp_f32_e32 v237, v237
	v_exp_f32_e32 v238, v238
	v_exp_f32_e32 v239, v239
	v_pk_add_f32 v[236:237], v[236:237], 1.0 op_sel_hi:[1,0]
	v_pk_add_f32 v[238:239], v[238:239], 1.0 op_sel_hi:[1,0]
	v_rcp_f32_e32 v236, v236
	v_rcp_f32_e32 v237, v237
	v_rcp_f32_e32 v238, v238
	v_rcp_f32_e32 v239, v239
	v_lshlrev_b32_e32 v232, 16, v174
	v_and_b32_e32 v233, 0xffff0000, v174
	v_lshlrev_b32_e32 v234, 16, v175
	v_and_b32_e32 v235, 0xffff0000, v175
	v_pk_fma_f32 v[96:97], v[236:237], v[232:233], v[164:165]
	v_pk_fma_f32 v[98:99], v[238:239], v[234:235], v[166:167]
	v_pk_mul_f32 v[236:237], v[96:97], v[96:97]
	v_pk_mul_f32 v[238:239], v[98:99], v[98:99]
	v_add_f32_e32 v229, v229, v236
	v_add_f32_e32 v229, v229, v237
	v_add_f32_e32 v229, v229, v238
	v_add_f32_e32 v229, v229, v239
	v_xor_b32_e32 v232, 64, v224
	ds_bpermute_b32 v233, v232, v229
	s_waitcnt lgkmcnt(0)
	v_add_f32_e32 v229, v229, v233
	v_xor_b32_e32 v232, 0x80, v224
	ds_bpermute_b32 v233, v232, v229
	s_waitcnt lgkmcnt(0)
	v_add_f32_e32 v229, v229, v233
	s_and_saveexec_b64 s[100:101], s[98:99]
	global_atomic_add_f32 v226, v229, s[16:17] offset:64
	s_mov_b64 exec, s[100:101]
	v_add_u32_e32 v232, 0x80000, v243
	v_lshrrev_b32_e32 v233, 1, v232
	global_load_dword v176, v226, s[14:15] offset:512
	global_load_dwordx4 v[128:131], v232, s[52:53]
	global_load_dwordx4 v[132:135], v232, s[52:53] offset:16
	global_load_dwordx4 v[136:139], v232, s[52:53] offset:512
	global_load_dwordx4 v[140:143], v232, s[52:53] offset:528
	global_load_dwordx4 v[144:147], v233, s[72:73]
	global_load_dwordx4 v[148:151], v233, s[72:73] offset:256
	v_add_u32_e32 v232, 0x90000, v243
	v_lshrrev_b32_e32 v233, 1, v232
	global_load_dword v177, v226, s[14:15] offset:576
	global_load_dwordx4 v[152:155], v232, s[52:53]
	global_load_dwordx4 v[156:159], v232, s[52:53] offset:16
	global_load_dwordx4 v[160:163], v232, s[52:53] offset:512
	global_load_dwordx4 v[164:167], v232, s[52:53] offset:528
	global_load_dwordx4 v[168:171], v233, s[72:73]
	global_load_dwordx4 v[172:175], v233, s[72:73] offset:256
	s_waitcnt vmcnt(23)
; __device__ __forceinline__ float bf_lo(unsigned w) { return __uint_as_float(w << 16); }
; __device__ __forceinline__ float bf_hi(unsigned w) { return __uint_as_float(w & 0xffff0000u); }
; __device__ __forceinline__ float sigmoidf_(float x) { return __builtin_amdgcn_rcpf(1.0f + __expf(-x)); }
; __device__ __forceinline__ float rinv_of(float ssq) { return rsqrtf(ssq * (1.0f / 1024.0f) + EPS); }
; __device__ __forceinline__ u32x4 pack8(const f32x4 a, const f32x4 b) { u32x4 w; w.x = cvt_pk_bf16(a[0], a[1]); w.y = cvt_pk_bf16(a[2], a[3]); w.z = cvt_pk_bf16(b[0], b[1]); w.w = cvt_pk_bf16(b[2], b[3]); return w; }
; __device__ __forceinline__ float sq8(const f32x4 a, const f32x4 b) { return (a[0] * a[0] + a[1] * a[1]) + (a[2] * a[2] + a[3] * a[3]) + (b[0] * b[0] + b[1] * b[1]) + (b[2] * b[2] + b[3] * b[3]); }
; __device__ __forceinline__ void ssq_commit(float s, float* ssq, int r, int fq) { s += __shfl_xor(s, 16); s += __shfl_xor(s, 32); if (fq == 0) atomicAdd(ssq + r, s); }
;     __device__ __forceinline__ void operator()(const AccT& acc, const pg8::Unit& u, int wr, int wc, int fr, int fq) const {
;     ...
;                 for (int mm = 0; mm < 2; ++mm) { const int m = 2 * mp + mm, r = EPI_ROW(u, ai, m); float s = 0.f; const float ri = rinv_of(rs[mm]);
; #pragma unroll
;                     for (int bj = 0; bj < 2; ++bj) { const int c = EPI_COL(u, bj); float* hp = h + (size_t)r * D + c; const u32x4 p4 = pw[mm][bj];
;                         const f32x4 a0 = acc[ai][bj][m][0] * ri, a1 = acc[ai][bj][m][1] * ri; f32x4 v0 = hv[mm][bj][0], v1 = hv[mm][bj][1];
;                         v0[0] += mul * sigmoidf_(a0[0]) * bf_lo(p4.x); v0[1] += mul * sigmoidf_(a0[1]) * bf_hi(p4.x); v0[2] += mul * sigmoidf_(a0[2]) * bf_lo(p4.y); v0[3] += mul * sigmoidf_(a0[3]) * bf_hi(p4.y);
;                         v1[0] += mul * sigmoidf_(a1[0]) * bf_lo(p4.z); v1[1] += mul * sigmoidf_(a1[1]) * bf_hi(p4.z); v1[2] += mul * sigmoidf_(a1[2]) * bf_lo(p4.w); v1[3] += mul * sigmoidf_(a1[3]) * bf_hi(p4.w);
;                         *(f32x4*)hp = v0; *(f32x4*)(hp + 4) = v1;
;                         if (hb) *(u32x4*)(hb + (size_t)r * D + c) = pack8(v0, v1);
;                         s += sq8(v0, v1); }
;                     ssq_commit(s, ssq, r, fq); }
	v_fmamk_f32 v230, v227, 0x3a800000, v225
	v_rsq_f32_e32 v230, v230
	v_mov_b32_e32 v229, 0
	v_mul_f32_e32 v230, 0xbfb8aa3b, v230
	v_pk_mul_f32 v[236:237], v[92:93], v[230:231] op_sel_hi:[1,0]
	v_pk_mul_f32 v[238:239], v[94:95], v[230:231] op_sel_hi:[1,0]
	v_exp_f32_e32 v236, v236
	v_exp_f32_e32 v237, v237
	v_exp_f32_e32 v238, v238
	v_exp_f32_e32 v239, v239
	v_pk_add_f32 v[236:237], v[236:237], 1.0 op_sel_hi:[1,0]
	v_pk_add_f32 v[238:239], v[238:239], 1.0 op_sel_hi:[1,0]
	v_rcp_f32_e32 v236, v236
	v_rcp_f32_e32 v237, v237
	v_rcp_f32_e32 v238, v238
	v_rcp_f32_e32 v239, v239
	v_lshlrev_b32_e32 v232, 16, v212
	v_and_b32_e32 v233, 0xffff0000, v212
	v_lshlrev_b32_e32 v234, 16, v213
	v_and_b32_e32 v235, 0xffff0000, v213
	v_pk_fma_f32 v[92:93], v[236:237], v[232:233], v[178:179]
	v_pk_fma_f32 v[94:95], v[238:239], v[234:235], v[180:181]
	v_pk_mul_f32 v[236:237], v[92:93], v[92:93]
	v_pk_mul_f32 v[238:239], v[94:95], v[94:95]
	v_add_f32_e32 v229, v229, v236
	v_add_f32_e32 v229, v229, v237
	v_add_f32_e32 v229, v229, v238
	v_add_f32_e32 v229, v229, v239
	v_pk_mul_f32 v[236:237], v[88:89], v[230:231] op_sel_hi:[1,0]
	v_pk_mul_f32 v[238:239], v[90:91], v[230:231] op_sel_hi:[1,0]
	v_exp_f32_e32 v236, v236
	v_exp_f32_e32 v237, v237
	v_exp_f32_e32 v238, v238
	v_exp_f32_e32 v239, v239
	v_pk_add_f32 v[236:237], v[236:237], 1.0 op_sel_hi:[1,0]
	v_pk_add_f32 v[238:239], v[238:239], 1.0 op_sel_hi:[1,0]
	v_rcp_f32_e32 v236, v236
	v_rcp_f32_e32 v237, v237
	v_rcp_f32_e32 v238, v238
	v_rcp_f32_e32 v239, v239
	v_lshlrev_b32_e32 v232, 16, v214
	v_and_b32_e32 v233, 0xffff0000, v214
	v_lshlrev_b32_e32 v234, 16, v215
	v_and_b32_e32 v235, 0xffff0000, v215
	v_pk_fma_f32 v[88:89], v[236:237], v[232:233], v[182:183]
	v_pk_fma_f32 v[90:91], v[238:239], v[234:235], v[184:185]
	v_pk_mul_f32 v[236:237], v[88:89], v[88:89]
	v_pk_mul_f32 v[238:239], v[90:91], v[90:91]
	v_add_f32_e32 v229, v229, v236
	v_add_f32_e32 v229, v229, v237
	v_add_f32_e32 v229, v229, v238
	v_add_f32_e32 v229, v229, v239
	v_pk_mul_f32 v[236:237], v[84:85], v[230:231] op_sel_hi:[1,0]
	v_pk_mul_f32 v[238:239], v[86:87], v[230:231] op_sel_hi:[1,0]
	v_exp_f32_e32 v236, v236
	v_exp_f32_e32 v237, v237
	v_exp_f32_e32 v238, v238
	v_exp_f32_e32 v239, v239
	v_pk_add_f32 v[236:237], v[236:237], 1.0 op_sel_hi:[1,0]
	v_pk_add_f32 v[238:239], v[238:239], 1.0 op_sel_hi:[1,0]
	v_rcp_f32_e32 v236, v236
	v_rcp_f32_e32 v237, v237
	v_rcp_f32_e32 v238, v238
	v_rcp_f32_e32 v239, v239
	v_lshlrev_b32_e32 v232, 16, v216
	v_and_b32_e32 v233, 0xffff0000, v216
	v_lshlrev_b32_e32 v234, 16, v217
	v_and_b32_e32 v235, 0xffff0000, v217
	v_pk_fma_f32 v[84:85], v[236:237], v[232:233], v[186:187]
	v_pk_fma_f32 v[86:87], v[238:239], v[234:235], v[188:189]
	v_pk_mul_f32 v[236:237], v[84:85], v[84:85]
	v_pk_mul_f32 v[238:239], v[86:87], v[86:87]
	v_add_f32_e32 v229, v229, v236
	v_add_f32_e32 v229, v229, v237
	v_add_f32_e32 v229, v229, v238
	v_add_f32_e32 v229, v229, v239
	v_pk_mul_f32 v[236:237], v[80:81], v[230:231] op_sel_hi:[1,0]
	v_pk_mul_f32 v[238:239], v[82:83], v[230:231] op_sel_hi:[1,0]
	v_exp_f32_e32 v236, v236
	v_exp_f32_e32 v237, v237
	v_exp_f32_e32 v238, v238
	v_exp_f32_e32 v239, v239
	v_pk_add_f32 v[236:237], v[236:237], 1.0 op_sel_hi:[1,0]
	v_pk_add_f32 v[238:239], v[238:239], 1.0 op_sel_hi:[1,0]
	v_rcp_f32_e32 v236, v236
	v_rcp_f32_e32 v237, v237
	v_rcp_f32_e32 v238, v238
	v_rcp_f32_e32 v239, v239
	v_lshlrev_b32_e32 v232, 16, v218
	v_and_b32_e32 v233, 0xffff0000, v218
	v_lshlrev_b32_e32 v234, 16, v219
	v_and_b32_e32 v235, 0xffff0000, v219
	v_pk_fma_f32 v[80:81], v[236:237], v[232:233], v[190:191]
	v_pk_fma_f32 v[82:83], v[238:239], v[234:235], v[192:193]
	v_pk_mul_f32 v[236:237], v[80:81], v[80:81]
	v_pk_mul_f32 v[238:239], v[82:83], v[82:83]
	v_add_f32_e32 v229, v229, v236
	v_add_f32_e32 v229, v229, v237
	v_add_f32_e32 v229, v229, v238
	v_add_f32_e32 v229, v229, v239
	v_xor_b32_e32 v232, 64, v224
	ds_bpermute_b32 v233, v232, v229
	s_waitcnt lgkmcnt(0)
	v_add_f32_e32 v229, v229, v233
	v_xor_b32_e32 v232, 0x80, v224
	ds_bpermute_b32 v233, v232, v229
	s_waitcnt lgkmcnt(0)
	v_add_f32_e32 v229, v229, v233
	s_and_saveexec_b64 s[100:101], s[98:99]
	global_atomic_add_f32 v226, v229, s[16:17] offset:128
	s_mov_b64 exec, s[100:101]
	s_waitcnt vmcnt(17)
; __device__ __forceinline__ float bf_lo(unsigned w) { return __uint_as_float(w << 16); }
; __device__ __forceinline__ float bf_hi(unsigned w) { return __uint_as_float(w & 0xffff0000u); }
; __device__ __forceinline__ float sigmoidf_(float x) { return __builtin_amdgcn_rcpf(1.0f + __expf(-x)); }
; __device__ __forceinline__ float rinv_of(float ssq) { return rsqrtf(ssq * (1.0f / 1024.0f) + EPS); }
; __device__ __forceinline__ u32x4 pack8(const f32x4 a, const f32x4 b) { u32x4 w; w.x = cvt_pk_bf16(a[0], a[1]); w.y = cvt_pk_bf16(a[2], a[3]); w.z = cvt_pk_bf16(b[0], b[1]); w.w = cvt_pk_bf16(b[2], b[3]); return w; }
; __device__ __forceinline__ float sq8(const f32x4 a, const f32x4 b) { return (a[0] * a[0] + a[1] * a[1]) + (a[2] * a[2] + a[3] * a[3]) + (b[0] * b[0] + b[1] * b[1]) + (b[2] * b[2] + b[3] * b[3]); }
; __device__ __forceinline__ void ssq_commit(float s, float* ssq, int r, int fq) { s += __shfl_xor(s, 16); s += __shfl_xor(s, 32); if (fq == 0) atomicAdd(ssq + r, s); }
;     __device__ __forceinline__ void operator()(const AccT& acc, const pg8::Unit& u, int wr, int wc, int fr, int fq) const {
;     ...
;                 for (int mm = 0; mm < 2; ++mm) { const int m = 2 * mp + mm, r = EPI_ROW(u, ai, m); float s = 0.f; const float ri = rinv_of(rs[mm]);
; #pragma unroll
;                     for (int bj = 0; bj < 2; ++bj) { const int c = EPI_COL(u, bj); float* hp = h + (size_t)r * D + c; const u32x4 p4 = pw[mm][bj];
;                         const f32x4 a0 = acc[ai][bj][m][0] * ri, a1 = acc[ai][bj][m][1] * ri; f32x4 v0 = hv[mm][bj][0], v1 = hv[mm][bj][1];
;                         v0[0] += mul * sigmoidf_(a0[0]) * bf_lo(p4.x); v0[1] += mul * sigmoidf_(a0[1]) * bf_hi(p4.x); v0[2] += mul * sigmoidf_(a0[2]) * bf_lo(p4.y); v0[3] += mul * sigmoidf_(a0[3]) * bf_hi(p4.y);
;                         v1[0] += mul * sigmoidf_(a1[0]) * bf_lo(p4.z); v1[1] += mul * sigmoidf_(a1[1]) * bf_hi(p4.z); v1[2] += mul * sigmoidf_(a1[2]) * bf_lo(p4.w); v1[3] += mul * sigmoidf_(a1[3]) * bf_hi(p4.w);
;                         *(f32x4*)hp = v0; *(f32x4*)(hp + 4) = v1;
;                         if (hb) *(u32x4*)(hb + (size_t)r * D + c) = pack8(v0, v1);
;                         s += sq8(v0, v1); }
;                     ssq_commit(s, ssq, r, fq); }
	v_fmamk_f32 v230, v228, 0x3a800000, v225
	v_rsq_f32_e32 v230, v230
	v_mov_b32_e32 v229, 0
	v_mul_f32_e32 v230, 0xbfb8aa3b, v230
	v_pk_mul_f32 v[236:237], v[76:77], v[230:231] op_sel_hi:[1,0]
	v_pk_mul_f32 v[238:239], v[78:79], v[230:231] op_sel_hi:[1,0]
	v_exp_f32_e32 v236, v236
	v_exp_f32_e32 v237, v237
	v_exp_f32_e32 v238, v238
	v_exp_f32_e32 v239, v239
	v_pk_add_f32 v[236:237], v[236:237], 1.0 op_sel_hi:[1,0]
	v_pk_add_f32 v[238:239], v[238:239], 1.0 op_sel_hi:[1,0]
	v_rcp_f32_e32 v236, v236
	v_rcp_f32_e32 v237, v237
	v_rcp_f32_e32 v238, v238
	v_rcp_f32_e32 v239, v239
	v_lshlrev_b32_e32 v232, 16, v220
	v_and_b32_e32 v233, 0xffff0000, v220
	v_lshlrev_b32_e32 v234, 16, v221
	v_and_b32_e32 v235, 0xffff0000, v221
	v_pk_fma_f32 v[76:77], v[236:237], v[232:233], v[194:195]
	v_pk_fma_f32 v[78:79], v[238:239], v[234:235], v[196:197]
	v_pk_mul_f32 v[236:237], v[76:77], v[76:77]
	v_pk_mul_f32 v[238:239], v[78:79], v[78:79]
	v_add_f32_e32 v229, v229, v236
	v_add_f32_e32 v229, v229, v237
	v_add_f32_e32 v229, v229, v238
	v_add_f32_e32 v229, v229, v239
	v_pk_mul_f32 v[236:237], v[72:73], v[230:231] op_sel_hi:[1,0]
	v_pk_mul_f32 v[238:239], v[74:75], v[230:231] op_sel_hi:[1,0]
	v_exp_f32_e32 v236, v236
	v_exp_f32_e32 v237, v237
	v_exp_f32_e32 v238, v238
	v_exp_f32_e32 v239, v239
	v_pk_add_f32 v[236:237], v[236:237], 1.0 op_sel_hi:[1,0]
	v_pk_add_f32 v[238:239], v[238:239], 1.0 op_sel_hi:[1,0]
	v_rcp_f32_e32 v236, v236
	v_rcp_f32_e32 v237, v237
	v_rcp_f32_e32 v238, v238
	v_rcp_f32_e32 v239, v239
	v_lshlrev_b32_e32 v232, 16, v222
	v_and_b32_e32 v233, 0xffff0000, v222
	v_lshlrev_b32_e32 v234, 16, v223
	v_and_b32_e32 v235, 0xffff0000, v223
	v_pk_fma_f32 v[72:73], v[236:237], v[232:233], v[198:199]
	v_pk_fma_f32 v[74:75], v[238:239], v[234:235], v[200:201]
	v_pk_mul_f32 v[236:237], v[72:73], v[72:73]
	v_pk_mul_f32 v[238:239], v[74:75], v[74:75]
	v_add_f32_e32 v229, v229, v236
	v_add_f32_e32 v229, v229, v237
	v_add_f32_e32 v229, v229, v238
	v_add_f32_e32 v229, v229, v239
	v_pk_mul_f32 v[236:237], v[68:69], v[230:231] op_sel_hi:[1,0]
	v_pk_mul_f32 v[238:239], v[70:71], v[230:231] op_sel_hi:[1,0]
	v_exp_f32_e32 v236, v236
	v_exp_f32_e32 v237, v237
	v_exp_f32_e32 v238, v238
	v_exp_f32_e32 v239, v239
	v_pk_add_f32 v[236:237], v[236:237], 1.0 op_sel_hi:[1,0]
	v_pk_add_f32 v[238:239], v[238:239], 1.0 op_sel_hi:[1,0]
	v_rcp_f32_e32 v236, v236
	v_rcp_f32_e32 v237, v237
	v_rcp_f32_e32 v238, v238
	v_rcp_f32_e32 v239, v239
	v_lshlrev_b32_e32 v232, 16, v244
	v_and_b32_e32 v233, 0xffff0000, v244
	v_lshlrev_b32_e32 v234, 16, v245
	v_and_b32_e32 v235, 0xffff0000, v245
	v_pk_fma_f32 v[68:69], v[236:237], v[232:233], v[202:203]
	v_pk_fma_f32 v[70:71], v[238:239], v[234:235], v[204:205]
	v_pk_mul_f32 v[236:237], v[68:69], v[68:69]
	v_pk_mul_f32 v[238:239], v[70:71], v[70:71]
	v_add_f32_e32 v229, v229, v236
	v_add_f32_e32 v229, v229, v237
	v_add_f32_e32 v229, v229, v238
	v_add_f32_e32 v229, v229, v239
	v_pk_mul_f32 v[236:237], v[64:65], v[230:231] op_sel_hi:[1,0]
	v_pk_mul_f32 v[238:239], v[66:67], v[230:231] op_sel_hi:[1,0]
	v_exp_f32_e32 v236, v236
	v_exp_f32_e32 v237, v237
	v_exp_f32_e32 v238, v238
	v_exp_f32_e32 v239, v239
	v_pk_add_f32 v[236:237], v[236:237], 1.0 op_sel_hi:[1,0]
	v_pk_add_f32 v[238:239], v[238:239], 1.0 op_sel_hi:[1,0]
	v_rcp_f32_e32 v236, v236
	v_rcp_f32_e32 v237, v237
	v_rcp_f32_e32 v238, v238
	v_rcp_f32_e32 v239, v239
	v_lshlrev_b32_e32 v232, 16, v246
	v_and_b32_e32 v233, 0xffff0000, v246
	v_lshlrev_b32_e32 v234, 16, v247
	v_and_b32_e32 v235, 0xffff0000, v247
	v_pk_fma_f32 v[64:65], v[236:237], v[232:233], v[206:207]
	v_pk_fma_f32 v[66:67], v[238:239], v[234:235], v[208:209]
	v_pk_mul_f32 v[236:237], v[64:65], v[64:65]
	v_pk_mul_f32 v[238:239], v[66:67], v[66:67]
	v_add_f32_e32 v229, v229, v236
	v_add_f32_e32 v229, v229, v237
	v_add_f32_e32 v229, v229, v238
	v_add_f32_e32 v229, v229, v239
	v_xor_b32_e32 v232, 64, v224
	ds_bpermute_b32 v233, v232, v229
	s_waitcnt lgkmcnt(0)
	v_add_f32_e32 v229, v229, v233
	v_xor_b32_e32 v232, 0x80, v224
	ds_bpermute_b32 v233, v232, v229
	s_waitcnt lgkmcnt(0)
	v_add_f32_e32 v229, v229, v233
	s_and_saveexec_b64 s[100:101], s[98:99]
	global_atomic_add_f32 v226, v229, s[16:17] offset:192
	s_mov_b64 exec, s[100:101]
	v_add_u32_e32 v232, 0xa0000, v243
	v_lshrrev_b32_e32 v233, 1, v232
	global_load_dword v227, v226, s[14:15] offset:640
	global_load_dwordx4 v[178:181], v232, s[52:53]
	global_load_dwordx4 v[182:185], v232, s[52:53] offset:16
	global_load_dwordx4 v[186:189], v232, s[52:53] offset:512
	global_load_dwordx4 v[190:193], v232, s[52:53] offset:528
	global_load_dwordx4 v[212:215], v233, s[72:73]
	global_load_dwordx4 v[216:219], v233, s[72:73] offset:256
	v_add_u32_e32 v232, 0xb0000, v243
	v_lshrrev_b32_e32 v233, 1, v232
	global_load_dword v228, v226, s[14:15] offset:704
	global_load_dwordx4 v[194:197], v232, s[52:53]
	global_load_dwordx4 v[198:201], v232, s[52:53] offset:16
	global_load_dwordx4 v[202:205], v232, s[52:53] offset:512
	global_load_dwordx4 v[206:209], v232, s[52:53] offset:528
	global_load_dwordx4 v[220:223], v233, s[72:73]
	global_load_dwordx4 v[244:247], v233, s[72:73] offset:256
	s_waitcnt vmcnt(23)
; __device__ __forceinline__ float bf_lo(unsigned w) { return __uint_as_float(w << 16); }
; __device__ __forceinline__ float bf_hi(unsigned w) { return __uint_as_float(w & 0xffff0000u); }
; __device__ __forceinline__ float sigmoidf_(float x) { return __builtin_amdgcn_rcpf(1.0f + __expf(-x)); }
; __device__ __forceinline__ float rinv_of(float ssq) { return rsqrtf(ssq * (1.0f / 1024.0f) + EPS); }
; __device__ __forceinline__ u32x4 pack8(const f32x4 a, const f32x4 b) { u32x4 w; w.x = cvt_pk_bf16(a[0], a[1]); w.y = cvt_pk_bf16(a[2], a[3]); w.z = cvt_pk_bf16(b[0], b[1]); w.w = cvt_pk_bf16(b[2], b[3]); return w; }
; __device__ __forceinline__ float sq8(const f32x4 a, const f32x4 b) { return (a[0] * a[0] + a[1] * a[1]) + (a[2] * a[2] + a[3] * a[3]) + (b[0] * b[0] + b[1] * b[1]) + (b[2] * b[2] + b[3] * b[3]); }
; __device__ __forceinline__ void ssq_commit(float s, float* ssq, int r, int fq) { s += __shfl_xor(s, 16); s += __shfl_xor(s, 32); if (fq == 0) atomicAdd(ssq + r, s); }
;     __device__ __forceinline__ void operator()(const AccT& acc, const pg8::Unit& u, int wr, int wc, int fr, int fq) const {
;     ...
;                 for (int mm = 0; mm < 2; ++mm) { const int m = 2 * mp + mm, r = EPI_ROW(u, ai, m); float s = 0.f; const float ri = rinv_of(rs[mm]);
; #pragma unroll
;                     for (int bj = 0; bj < 2; ++bj) { const int c = EPI_COL(u, bj); float* hp = h + (size_t)r * D + c; const u32x4 p4 = pw[mm][bj];
;                         const f32x4 a0 = acc[ai][bj][m][0] * ri, a1 = acc[ai][bj][m][1] * ri; f32x4 v0 = hv[mm][bj][0], v1 = hv[mm][bj][1];
;                         v0[0] += mul * sigmoidf_(a0[0]) * bf_lo(p4.x); v0[1] += mul * sigmoidf_(a0[1]) * bf_hi(p4.x); v0[2] += mul * sigmoidf_(a0[2]) * bf_lo(p4.y); v0[3] += mul * sigmoidf_(a0[3]) * bf_hi(p4.y);
;                         v1[0] += mul * sigmoidf_(a1[0]) * bf_lo(p4.z); v1[1] += mul * sigmoidf_(a1[1]) * bf_hi(p4.z); v1[2] += mul * sigmoidf_(a1[2]) * bf_lo(p4.w); v1[3] += mul * sigmoidf_(a1[3]) * bf_hi(p4.w);
;                         *(f32x4*)hp = v0; *(f32x4*)(hp + 4) = v1;
;                         if (hb) *(u32x4*)(hb + (size_t)r * D + c) = pack8(v0, v1);
;                         s += sq8(v0, v1); }
;                     ssq_commit(s, ssq, r, fq); }
	v_fmamk_f32 v230, v176, 0x3a800000, v225
	v_rsq_f32_e32 v230, v230
	v_mov_b32_e32 v229, 0
	v_mul_f32_e32 v230, 0xbfb8aa3b, v230
	v_pk_mul_f32 v[236:237], v[60:61], v[230:231] op_sel_hi:[1,0]
	v_pk_mul_f32 v[238:239], v[62:63], v[230:231] op_sel_hi:[1,0]
	v_exp_f32_e32 v236, v236
	v_exp_f32_e32 v237, v237
	v_exp_f32_e32 v238, v238
	v_exp_f32_e32 v239, v239
	v_pk_add_f32 v[236:237], v[236:237], 1.0 op_sel_hi:[1,0]
	v_pk_add_f32 v[238:239], v[238:239], 1.0 op_sel_hi:[1,0]
	v_rcp_f32_e32 v236, v236
	v_rcp_f32_e32 v237, v237
	v_rcp_f32_e32 v238, v238
	v_rcp_f32_e32 v239, v239
	v_lshlrev_b32_e32 v232, 16, v144
	v_and_b32_e32 v233, 0xffff0000, v144
	v_lshlrev_b32_e32 v234, 16, v145
	v_and_b32_e32 v235, 0xffff0000, v145
	v_pk_fma_f32 v[60:61], v[236:237], v[232:233], v[128:129]
	v_pk_fma_f32 v[62:63], v[238:239], v[234:235], v[130:131]
	v_pk_mul_f32 v[236:237], v[60:61], v[60:61]
	v_pk_mul_f32 v[238:239], v[62:63], v[62:63]
	v_add_f32_e32 v229, v229, v236
	v_add_f32_e32 v229, v229, v237
	v_add_f32_e32 v229, v229, v238
	v_add_f32_e32 v229, v229, v239
	v_pk_mul_f32 v[236:237], v[56:57], v[230:231] op_sel_hi:[1,0]
	v_pk_mul_f32 v[238:239], v[58:59], v[230:231] op_sel_hi:[1,0]
	v_exp_f32_e32 v236, v236
	v_exp_f32_e32 v237, v237
	v_exp_f32_e32 v238, v238
	v_exp_f32_e32 v239, v239
	v_pk_add_f32 v[236:237], v[236:237], 1.0 op_sel_hi:[1,0]
	v_pk_add_f32 v[238:239], v[238:239], 1.0 op_sel_hi:[1,0]
	v_rcp_f32_e32 v236, v236
	v_rcp_f32_e32 v237, v237
	v_rcp_f32_e32 v238, v238
	v_rcp_f32_e32 v239, v239
	v_lshlrev_b32_e32 v232, 16, v146
	v_and_b32_e32 v233, 0xffff0000, v146
	v_lshlrev_b32_e32 v234, 16, v147
	v_and_b32_e32 v235, 0xffff0000, v147
	v_pk_fma_f32 v[56:57], v[236:237], v[232:233], v[132:133]
	v_pk_fma_f32 v[58:59], v[238:239], v[234:235], v[134:135]
	v_pk_mul_f32 v[236:237], v[56:57], v[56:57]
	v_pk_mul_f32 v[238:239], v[58:59], v[58:59]
	v_add_f32_e32 v229, v229, v236
	v_add_f32_e32 v229, v229, v237
	v_add_f32_e32 v229, v229, v238
	v_add_f32_e32 v229, v229, v239
	v_pk_mul_f32 v[236:237], v[52:53], v[230:231] op_sel_hi:[1,0]
	v_pk_mul_f32 v[238:239], v[54:55], v[230:231] op_sel_hi:[1,0]
	v_exp_f32_e32 v236, v236
	v_exp_f32_e32 v237, v237
	v_exp_f32_e32 v238, v238
	v_exp_f32_e32 v239, v239
	v_pk_add_f32 v[236:237], v[236:237], 1.0 op_sel_hi:[1,0]
	v_pk_add_f32 v[238:239], v[238:239], 1.0 op_sel_hi:[1,0]
	v_rcp_f32_e32 v236, v236
	v_rcp_f32_e32 v237, v237
	v_rcp_f32_e32 v238, v238
	v_rcp_f32_e32 v239, v239
	v_lshlrev_b32_e32 v232, 16, v148
	v_and_b32_e32 v233, 0xffff0000, v148
	v_lshlrev_b32_e32 v234, 16, v149
	v_and_b32_e32 v235, 0xffff0000, v149
	v_pk_fma_f32 v[52:53], v[236:237], v[232:233], v[136:137]
	v_pk_fma_f32 v[54:55], v[238:239], v[234:235], v[138:139]
	v_pk_mul_f32 v[236:237], v[52:53], v[52:53]
	v_pk_mul_f32 v[238:239], v[54:55], v[54:55]
	v_add_f32_e32 v229, v229, v236
	v_add_f32_e32 v229, v229, v237
	v_add_f32_e32 v229, v229, v238
	v_add_f32_e32 v229, v229, v239
	v_pk_mul_f32 v[236:237], v[48:49], v[230:231] op_sel_hi:[1,0]
	v_pk_mul_f32 v[238:239], v[50:51], v[230:231] op_sel_hi:[1,0]
	v_exp_f32_e32 v236, v236
	v_exp_f32_e32 v237, v237
	v_exp_f32_e32 v238, v238
	v_exp_f32_e32 v239, v239
	v_pk_add_f32 v[236:237], v[236:237], 1.0 op_sel_hi:[1,0]
	v_pk_add_f32 v[238:239], v[238:239], 1.0 op_sel_hi:[1,0]
	v_rcp_f32_e32 v236, v236
	v_rcp_f32_e32 v237, v237
	v_rcp_f32_e32 v238, v238
	v_rcp_f32_e32 v239, v239
	v_lshlrev_b32_e32 v232, 16, v150
	v_and_b32_e32 v233, 0xffff0000, v150
	v_lshlrev_b32_e32 v234, 16, v151
	v_and_b32_e32 v235, 0xffff0000, v151
	v_pk_fma_f32 v[48:49], v[236:237], v[232:233], v[140:141]
	v_pk_fma_f32 v[50:51], v[238:239], v[234:235], v[142:143]
	v_pk_mul_f32 v[236:237], v[48:49], v[48:49]
	v_pk_mul_f32 v[238:239], v[50:51], v[50:51]
	v_add_f32_e32 v229, v229, v236
	v_add_f32_e32 v229, v229, v237
	v_add_f32_e32 v229, v229, v238
	v_add_f32_e32 v229, v229, v239
	v_xor_b32_e32 v232, 64, v224
	ds_bpermute_b32 v233, v232, v229
	s_waitcnt lgkmcnt(0)
	v_add_f32_e32 v229, v229, v233
	v_xor_b32_e32 v232, 0x80, v224
	ds_bpermute_b32 v233, v232, v229
	s_waitcnt lgkmcnt(0)
	v_add_f32_e32 v229, v229, v233
	s_and_saveexec_b64 s[100:101], s[98:99]
	global_atomic_add_f32 v226, v229, s[16:17] offset:512
	s_mov_b64 exec, s[100:101]
	s_waitcnt vmcnt(17)
; __device__ __forceinline__ float bf_lo(unsigned w) { return __uint_as_float(w << 16); }
; __device__ __forceinline__ float bf_hi(unsigned w) { return __uint_as_float(w & 0xffff0000u); }
; __device__ __forceinline__ float sigmoidf_(float x) { return __builtin_amdgcn_rcpf(1.0f + __expf(-x)); }
; __device__ __forceinline__ float rinv_of(float ssq) { return rsqrtf(ssq * (1.0f / 1024.0f) + EPS); }
; __device__ __forceinline__ u32x4 pack8(const f32x4 a, const f32x4 b) { u32x4 w; w.x = cvt_pk_bf16(a[0], a[1]); w.y = cvt_pk_bf16(a[2], a[3]); w.z = cvt_pk_bf16(b[0], b[1]); w.w = cvt_pk_bf16(b[2], b[3]); return w; }
; __device__ __forceinline__ float sq8(const f32x4 a, const f32x4 b) { return (a[0] * a[0] + a[1] * a[1]) + (a[2] * a[2] + a[3] * a[3]) + (b[0] * b[0] + b[1] * b[1]) + (b[2] * b[2] + b[3] * b[3]); }
; __device__ __forceinline__ void ssq_commit(float s, float* ssq, int r, int fq) { s += __shfl_xor(s, 16); s += __shfl_xor(s, 32); if (fq == 0) atomicAdd(ssq + r, s); }
;     __device__ __forceinline__ void operator()(const AccT& acc, const pg8::Unit& u, int wr, int wc, int fr, int fq) const {
;     ...
;                 for (int mm = 0; mm < 2; ++mm) { const int m = 2 * mp + mm, r = EPI_ROW(u, ai, m); float s = 0.f; const float ri = rinv_of(rs[mm]);
; #pragma unroll
;                     for (int bj = 0; bj < 2; ++bj) { const int c = EPI_COL(u, bj); float* hp = h + (size_t)r * D + c; const u32x4 p4 = pw[mm][bj];
;                         const f32x4 a0 = acc[ai][bj][m][0] * ri, a1 = acc[ai][bj][m][1] * ri; f32x4 v0 = hv[mm][bj][0], v1 = hv[mm][bj][1];
;                         v0[0] += mul * sigmoidf_(a0[0]) * bf_lo(p4.x); v0[1] += mul * sigmoidf_(a0[1]) * bf_hi(p4.x); v0[2] += mul * sigmoidf_(a0[2]) * bf_lo(p4.y); v0[3] += mul * sigmoidf_(a0[3]) * bf_hi(p4.y);
;                         v1[0] += mul * sigmoidf_(a1[0]) * bf_lo(p4.z); v1[1] += mul * sigmoidf_(a1[1]) * bf_hi(p4.z); v1[2] += mul * sigmoidf_(a1[2]) * bf_lo(p4.w); v1[3] += mul * sigmoidf_(a1[3]) * bf_hi(p4.w);
;                         *(f32x4*)hp = v0; *(f32x4*)(hp + 4) = v1;
;                         if (hb) *(u32x4*)(hb + (size_t)r * D + c) = pack8(v0, v1);
;                         s += sq8(v0, v1); }
;                     ssq_commit(s, ssq, r, fq); }
	v_fmamk_f32 v230, v177, 0x3a800000, v225
	v_rsq_f32_e32 v230, v230
	v_mov_b32_e32 v229, 0
	v_mul_f32_e32 v230, 0xbfb8aa3b, v230
	v_pk_mul_f32 v[236:237], v[44:45], v[230:231] op_sel_hi:[1,0]
	v_pk_mul_f32 v[238:239], v[46:47], v[230:231] op_sel_hi:[1,0]
	v_exp_f32_e32 v236, v236
	v_exp_f32_e32 v237, v237
	v_exp_f32_e32 v238, v238
	v_exp_f32_e32 v239, v239
	v_pk_add_f32 v[236:237], v[236:237], 1.0 op_sel_hi:[1,0]
	v_pk_add_f32 v[238:239], v[238:239], 1.0 op_sel_hi:[1,0]
	v_rcp_f32_e32 v236, v236
	v_rcp_f32_e32 v237, v237
	v_rcp_f32_e32 v238, v238
	v_rcp_f32_e32 v239, v239
	v_lshlrev_b32_e32 v232, 16, v168
	v_and_b32_e32 v233, 0xffff0000, v168
	v_lshlrev_b32_e32 v234, 16, v169
	v_and_b32_e32 v235, 0xffff0000, v169
	v_pk_fma_f32 v[44:45], v[236:237], v[232:233], v[152:153]
	v_pk_fma_f32 v[46:47], v[238:239], v[234:235], v[154:155]
	v_pk_mul_f32 v[236:237], v[44:45], v[44:45]
	v_pk_mul_f32 v[238:239], v[46:47], v[46:47]
	v_add_f32_e32 v229, v229, v236
	v_add_f32_e32 v229, v229, v237
	v_add_f32_e32 v229, v229, v238
	v_add_f32_e32 v229, v229, v239
	v_pk_mul_f32 v[236:237], v[40:41], v[230:231] op_sel_hi:[1,0]
	v_pk_mul_f32 v[238:239], v[42:43], v[230:231] op_sel_hi:[1,0]
	v_exp_f32_e32 v236, v236
	v_exp_f32_e32 v237, v237
	v_exp_f32_e32 v238, v238
	v_exp_f32_e32 v239, v239
	v_pk_add_f32 v[236:237], v[236:237], 1.0 op_sel_hi:[1,0]
	v_pk_add_f32 v[238:239], v[238:239], 1.0 op_sel_hi:[1,0]
	v_rcp_f32_e32 v236, v236
	v_rcp_f32_e32 v237, v237
	v_rcp_f32_e32 v238, v238
	v_rcp_f32_e32 v239, v239
	v_lshlrev_b32_e32 v232, 16, v170
	v_and_b32_e32 v233, 0xffff0000, v170
	v_lshlrev_b32_e32 v234, 16, v171
	v_and_b32_e32 v235, 0xffff0000, v171
	v_pk_fma_f32 v[40:41], v[236:237], v[232:233], v[156:157]
	v_pk_fma_f32 v[42:43], v[238:239], v[234:235], v[158:159]
	v_pk_mul_f32 v[236:237], v[40:41], v[40:41]
	v_pk_mul_f32 v[238:239], v[42:43], v[42:43]
	v_add_f32_e32 v229, v229, v236
	v_add_f32_e32 v229, v229, v237
	v_add_f32_e32 v229, v229, v238
	v_add_f32_e32 v229, v229, v239
	v_pk_mul_f32 v[236:237], v[36:37], v[230:231] op_sel_hi:[1,0]
	v_pk_mul_f32 v[238:239], v[38:39], v[230:231] op_sel_hi:[1,0]
	v_exp_f32_e32 v236, v236
	v_exp_f32_e32 v237, v237
	v_exp_f32_e32 v238, v238
	v_exp_f32_e32 v239, v239
	v_pk_add_f32 v[236:237], v[236:237], 1.0 op_sel_hi:[1,0]
	v_pk_add_f32 v[238:239], v[238:239], 1.0 op_sel_hi:[1,0]
	v_rcp_f32_e32 v236, v236
	v_rcp_f32_e32 v237, v237
	v_rcp_f32_e32 v238, v238
	v_rcp_f32_e32 v239, v239
	v_lshlrev_b32_e32 v232, 16, v172
	v_and_b32_e32 v233, 0xffff0000, v172
	v_lshlrev_b32_e32 v234, 16, v173
	v_and_b32_e32 v235, 0xffff0000, v173
	v_pk_fma_f32 v[36:37], v[236:237], v[232:233], v[160:161]
	v_pk_fma_f32 v[38:39], v[238:239], v[234:235], v[162:163]
	v_pk_mul_f32 v[236:237], v[36:37], v[36:37]
	v_pk_mul_f32 v[238:239], v[38:39], v[38:39]
	v_add_f32_e32 v229, v229, v236
	v_add_f32_e32 v229, v229, v237
	v_add_f32_e32 v229, v229, v238
	v_add_f32_e32 v229, v229, v239
	v_pk_mul_f32 v[236:237], v[32:33], v[230:231] op_sel_hi:[1,0]
	v_pk_mul_f32 v[238:239], v[34:35], v[230:231] op_sel_hi:[1,0]
	v_exp_f32_e32 v236, v236
	v_exp_f32_e32 v237, v237
	v_exp_f32_e32 v238, v238
	v_exp_f32_e32 v239, v239
	v_pk_add_f32 v[236:237], v[236:237], 1.0 op_sel_hi:[1,0]
	v_pk_add_f32 v[238:239], v[238:239], 1.0 op_sel_hi:[1,0]
	v_rcp_f32_e32 v236, v236
	v_rcp_f32_e32 v237, v237
	v_rcp_f32_e32 v238, v238
	v_rcp_f32_e32 v239, v239
	v_lshlrev_b32_e32 v232, 16, v174
	v_and_b32_e32 v233, 0xffff0000, v174
	v_lshlrev_b32_e32 v234, 16, v175
	v_and_b32_e32 v235, 0xffff0000, v175
	v_pk_fma_f32 v[32:33], v[236:237], v[232:233], v[164:165]
	v_pk_fma_f32 v[34:35], v[238:239], v[234:235], v[166:167]
	v_pk_mul_f32 v[236:237], v[32:33], v[32:33]
	v_pk_mul_f32 v[238:239], v[34:35], v[34:35]
	v_add_f32_e32 v229, v229, v236
	v_add_f32_e32 v229, v229, v237
	v_add_f32_e32 v229, v229, v238
	v_add_f32_e32 v229, v229, v239
	v_xor_b32_e32 v232, 64, v224
	ds_bpermute_b32 v233, v232, v229
	s_waitcnt lgkmcnt(0)
	v_add_f32_e32 v229, v229, v233
	v_xor_b32_e32 v232, 0x80, v224
	ds_bpermute_b32 v233, v232, v229
	s_waitcnt lgkmcnt(0)
	v_add_f32_e32 v229, v229, v233
	s_and_saveexec_b64 s[100:101], s[98:99]
	global_atomic_add_f32 v226, v229, s[16:17] offset:576
	s_mov_b64 exec, s[100:101]
	s_waitcnt vmcnt(9)
; __device__ __forceinline__ float bf_lo(unsigned w) { return __uint_as_float(w << 16); }
; __device__ __forceinline__ float bf_hi(unsigned w) { return __uint_as_float(w & 0xffff0000u); }
; __device__ __forceinline__ float sigmoidf_(float x) { return __builtin_amdgcn_rcpf(1.0f + __expf(-x)); }
; __device__ __forceinline__ float rinv_of(float ssq) { return rsqrtf(ssq * (1.0f / 1024.0f) + EPS); }
; __device__ __forceinline__ u32x4 pack8(const f32x4 a, const f32x4 b) { u32x4 w; w.x = cvt_pk_bf16(a[0], a[1]); w.y = cvt_pk_bf16(a[2], a[3]); w.z = cvt_pk_bf16(b[0], b[1]); w.w = cvt_pk_bf16(b[2], b[3]); return w; }
; __device__ __forceinline__ float sq8(const f32x4 a, const f32x4 b) { return (a[0] * a[0] + a[1] * a[1]) + (a[2] * a[2] + a[3] * a[3]) + (b[0] * b[0] + b[1] * b[1]) + (b[2] * b[2] + b[3] * b[3]); }
; __device__ __forceinline__ void ssq_commit(float s, float* ssq, int r, int fq) { s += __shfl_xor(s, 16); s += __shfl_xor(s, 32); if (fq == 0) atomicAdd(ssq + r, s); }
;     __device__ __forceinline__ void operator()(const AccT& acc, const pg8::Unit& u, int wr, int wc, int fr, int fq) const {
;     ...
;                 for (int mm = 0; mm < 2; ++mm) { const int m = 2 * mp + mm, r = EPI_ROW(u, ai, m); float s = 0.f; const float ri = rinv_of(rs[mm]);
; #pragma unroll
;                     for (int bj = 0; bj < 2; ++bj) { const int c = EPI_COL(u, bj); float* hp = h + (size_t)r * D + c; const u32x4 p4 = pw[mm][bj];
;                         const f32x4 a0 = acc[ai][bj][m][0] * ri, a1 = acc[ai][bj][m][1] * ri; f32x4 v0 = hv[mm][bj][0], v1 = hv[mm][bj][1];
;                         v0[0] += mul * sigmoidf_(a0[0]) * bf_lo(p4.x); v0[1] += mul * sigmoidf_(a0[1]) * bf_hi(p4.x); v0[2] += mul * sigmoidf_(a0[2]) * bf_lo(p4.y); v0[3] += mul * sigmoidf_(a0[3]) * bf_hi(p4.y);
;                         v1[0] += mul * sigmoidf_(a1[0]) * bf_lo(p4.z); v1[1] += mul * sigmoidf_(a1[1]) * bf_hi(p4.z); v1[2] += mul * sigmoidf_(a1[2]) * bf_lo(p4.w); v1[3] += mul * sigmoidf_(a1[3]) * bf_hi(p4.w);
;                         *(f32x4*)hp = v0; *(f32x4*)(hp + 4) = v1;
;                         if (hb) *(u32x4*)(hb + (size_t)r * D + c) = pack8(v0, v1);
;                         s += sq8(v0, v1); }
;                     ssq_commit(s, ssq, r, fq); }
	v_fmamk_f32 v230, v227, 0x3a800000, v225
	v_rsq_f32_e32 v230, v230
	v_mov_b32_e32 v229, 0
	v_mul_f32_e32 v230, 0xbfb8aa3b, v230
	v_pk_mul_f32 v[236:237], v[28:29], v[230:231] op_sel_hi:[1,0]
	v_pk_mul_f32 v[238:239], v[30:31], v[230:231] op_sel_hi:[1,0]
	v_exp_f32_e32 v236, v236
	v_exp_f32_e32 v237, v237
	v_exp_f32_e32 v238, v238
	v_exp_f32_e32 v239, v239
	v_pk_add_f32 v[236:237], v[236:237], 1.0 op_sel_hi:[1,0]
	v_pk_add_f32 v[238:239], v[238:239], 1.0 op_sel_hi:[1,0]
	v_rcp_f32_e32 v236, v236
	v_rcp_f32_e32 v237, v237
	v_rcp_f32_e32 v238, v238
	v_rcp_f32_e32 v239, v239
	v_lshlrev_b32_e32 v232, 16, v212
	v_and_b32_e32 v233, 0xffff0000, v212
	v_lshlrev_b32_e32 v234, 16, v213
	v_and_b32_e32 v235, 0xffff0000, v213
	v_pk_fma_f32 v[28:29], v[236:237], v[232:233], v[178:179]
	v_pk_fma_f32 v[30:31], v[238:239], v[234:235], v[180:181]
	v_pk_mul_f32 v[236:237], v[28:29], v[28:29]
	v_pk_mul_f32 v[238:239], v[30:31], v[30:31]
	v_add_f32_e32 v229, v229, v236
	v_add_f32_e32 v229, v229, v237
	v_add_f32_e32 v229, v229, v238
	v_add_f32_e32 v229, v229, v239
	v_pk_mul_f32 v[236:237], v[24:25], v[230:231] op_sel_hi:[1,0]
	v_pk_mul_f32 v[238:239], v[26:27], v[230:231] op_sel_hi:[1,0]
	v_exp_f32_e32 v236, v236
	v_exp_f32_e32 v237, v237
	v_exp_f32_e32 v238, v238
	v_exp_f32_e32 v239, v239
	v_pk_add_f32 v[236:237], v[236:237], 1.0 op_sel_hi:[1,0]
	v_pk_add_f32 v[238:239], v[238:239], 1.0 op_sel_hi:[1,0]
	v_rcp_f32_e32 v236, v236
	v_rcp_f32_e32 v237, v237
	v_rcp_f32_e32 v238, v238
	v_rcp_f32_e32 v239, v239
	v_lshlrev_b32_e32 v232, 16, v214
	v_and_b32_e32 v233, 0xffff0000, v214
	v_lshlrev_b32_e32 v234, 16, v215
	v_and_b32_e32 v235, 0xffff0000, v215
	v_pk_fma_f32 v[24:25], v[236:237], v[232:233], v[182:183]
	v_pk_fma_f32 v[26:27], v[238:239], v[234:235], v[184:185]
	v_pk_mul_f32 v[236:237], v[24:25], v[24:25]
	v_pk_mul_f32 v[238:239], v[26:27], v[26:27]
	v_add_f32_e32 v229, v229, v236
	v_add_f32_e32 v229, v229, v237
	v_add_f32_e32 v229, v229, v238
	v_add_f32_e32 v229, v229, v239
	v_pk_mul_f32 v[236:237], v[20:21], v[230:231] op_sel_hi:[1,0]
	v_pk_mul_f32 v[238:239], v[22:23], v[230:231] op_sel_hi:[1,0]
	v_exp_f32_e32 v236, v236
	v_exp_f32_e32 v237, v237
	v_exp_f32_e32 v238, v238
	v_exp_f32_e32 v239, v239
	v_pk_add_f32 v[236:237], v[236:237], 1.0 op_sel_hi:[1,0]
	v_pk_add_f32 v[238:239], v[238:239], 1.0 op_sel_hi:[1,0]
	v_rcp_f32_e32 v236, v236
	v_rcp_f32_e32 v237, v237
	v_rcp_f32_e32 v238, v238
	v_rcp_f32_e32 v239, v239
	v_lshlrev_b32_e32 v232, 16, v216
	v_and_b32_e32 v233, 0xffff0000, v216
	v_lshlrev_b32_e32 v234, 16, v217
	v_and_b32_e32 v235, 0xffff0000, v217
	v_pk_fma_f32 v[20:21], v[236:237], v[232:233], v[186:187]
	v_pk_fma_f32 v[22:23], v[238:239], v[234:235], v[188:189]
	v_pk_mul_f32 v[236:237], v[20:21], v[20:21]
	v_pk_mul_f32 v[238:239], v[22:23], v[22:23]
	v_add_f32_e32 v229, v229, v236
	v_add_f32_e32 v229, v229, v237
	v_add_f32_e32 v229, v229, v238
	v_add_f32_e32 v229, v229, v239
	v_pk_mul_f32 v[236:237], v[16:17], v[230:231] op_sel_hi:[1,0]
	v_pk_mul_f32 v[238:239], v[18:19], v[230:231] op_sel_hi:[1,0]
	v_exp_f32_e32 v236, v236
	v_exp_f32_e32 v237, v237
	v_exp_f32_e32 v238, v238
	v_exp_f32_e32 v239, v239
	v_pk_add_f32 v[236:237], v[236:237], 1.0 op_sel_hi:[1,0]
	v_pk_add_f32 v[238:239], v[238:239], 1.0 op_sel_hi:[1,0]
	v_rcp_f32_e32 v236, v236
	v_rcp_f32_e32 v237, v237
	v_rcp_f32_e32 v238, v238
	v_rcp_f32_e32 v239, v239
	v_lshlrev_b32_e32 v232, 16, v218
	v_and_b32_e32 v233, 0xffff0000, v218
	v_lshlrev_b32_e32 v234, 16, v219
	v_and_b32_e32 v235, 0xffff0000, v219
	v_pk_fma_f32 v[16:17], v[236:237], v[232:233], v[190:191]
	v_pk_fma_f32 v[18:19], v[238:239], v[234:235], v[192:193]
	v_pk_mul_f32 v[236:237], v[16:17], v[16:17]
	v_pk_mul_f32 v[238:239], v[18:19], v[18:19]
	v_add_f32_e32 v229, v229, v236
	v_add_f32_e32 v229, v229, v237
	v_add_f32_e32 v229, v229, v238
	v_add_f32_e32 v229, v229, v239
	v_xor_b32_e32 v232, 64, v224
	ds_bpermute_b32 v233, v232, v229
	s_waitcnt lgkmcnt(0)
	v_add_f32_e32 v229, v229, v233
	v_xor_b32_e32 v232, 0x80, v224
	ds_bpermute_b32 v233, v232, v229
	s_waitcnt lgkmcnt(0)
	v_add_f32_e32 v229, v229, v233
	s_and_saveexec_b64 s[100:101], s[98:99]
	global_atomic_add_f32 v226, v229, s[16:17] offset:640
	s_mov_b64 exec, s[100:101]
	s_waitcnt vmcnt(3)
; __device__ __forceinline__ float bf_lo(unsigned w) { return __uint_as_float(w << 16); }
; __device__ __forceinline__ float bf_hi(unsigned w) { return __uint_as_float(w & 0xffff0000u); }
; __device__ __forceinline__ float sigmoidf_(float x) { return __builtin_amdgcn_rcpf(1.0f + __expf(-x)); }
; __device__ __forceinline__ float rinv_of(float ssq) { return rsqrtf(ssq * (1.0f / 1024.0f) + EPS); }
; __device__ __forceinline__ u32x4 pack8(const f32x4 a, const f32x4 b) { u32x4 w; w.x = cvt_pk_bf16(a[0], a[1]); w.y = cvt_pk_bf16(a[2], a[3]); w.z = cvt_pk_bf16(b[0], b[1]); w.w = cvt_pk_bf16(b[2], b[3]); return w; }
; __device__ __forceinline__ float sq8(const f32x4 a, const f32x4 b) { return (a[0] * a[0] + a[1] * a[1]) + (a[2] * a[2] + a[3] * a[3]) + (b[0] * b[0] + b[1] * b[1]) + (b[2] * b[2] + b[3] * b[3]); }
; __device__ __forceinline__ void ssq_commit(float s, float* ssq, int r, int fq) { s += __shfl_xor(s, 16); s += __shfl_xor(s, 32); if (fq == 0) atomicAdd(ssq + r, s); }
;     __device__ __forceinline__ void operator()(const AccT& acc, const pg8::Unit& u, int wr, int wc, int fr, int fq) const {
;     ...
;                 for (int mm = 0; mm < 2; ++mm) { const int m = 2 * mp + mm, r = EPI_ROW(u, ai, m); float s = 0.f; const float ri = rinv_of(rs[mm]);
; #pragma unroll
;                     for (int bj = 0; bj < 2; ++bj) { const int c = EPI_COL(u, bj); float* hp = h + (size_t)r * D + c; const u32x4 p4 = pw[mm][bj];
;                         const f32x4 a0 = acc[ai][bj][m][0] * ri, a1 = acc[ai][bj][m][1] * ri; f32x4 v0 = hv[mm][bj][0], v1 = hv[mm][bj][1];
;                         v0[0] += mul * sigmoidf_(a0[0]) * bf_lo(p4.x); v0[1] += mul * sigmoidf_(a0[1]) * bf_hi(p4.x); v0[2] += mul * sigmoidf_(a0[2]) * bf_lo(p4.y); v0[3] += mul * sigmoidf_(a0[3]) * bf_hi(p4.y);
;                         v1[0] += mul * sigmoidf_(a1[0]) * bf_lo(p4.z); v1[1] += mul * sigmoidf_(a1[1]) * bf_hi(p4.z); v1[2] += mul * sigmoidf_(a1[2]) * bf_lo(p4.w); v1[3] += mul * sigmoidf_(a1[3]) * bf_hi(p4.w);
;                         *(f32x4*)hp = v0; *(f32x4*)(hp + 4) = v1;
;                         if (hb) *(u32x4*)(hb + (size_t)r * D + c) = pack8(v0, v1);
;                         s += sq8(v0, v1); }
;                     ssq_commit(s, ssq, r, fq); }
	v_fmamk_f32 v230, v228, 0x3a800000, v225
	v_rsq_f32_e32 v230, v230
	v_mov_b32_e32 v229, 0
	v_mul_f32_e32 v230, 0xbfb8aa3b, v230
	v_pk_mul_f32 v[236:237], v[12:13], v[230:231] op_sel_hi:[1,0]
	v_pk_mul_f32 v[238:239], v[14:15], v[230:231] op_sel_hi:[1,0]
	v_exp_f32_e32 v236, v236
	v_exp_f32_e32 v237, v237
	v_exp_f32_e32 v238, v238
	v_exp_f32_e32 v239, v239
	v_pk_add_f32 v[236:237], v[236:237], 1.0 op_sel_hi:[1,0]
	v_pk_add_f32 v[238:239], v[238:239], 1.0 op_sel_hi:[1,0]
	v_rcp_f32_e32 v236, v236
	v_rcp_f32_e32 v237, v237
	v_rcp_f32_e32 v238, v238
	v_rcp_f32_e32 v239, v239
	v_lshlrev_b32_e32 v232, 16, v220
	v_and_b32_e32 v233, 0xffff0000, v220
	v_lshlrev_b32_e32 v234, 16, v221
	v_and_b32_e32 v235, 0xffff0000, v221
	v_pk_fma_f32 v[12:13], v[236:237], v[232:233], v[194:195]
	v_pk_fma_f32 v[14:15], v[238:239], v[234:235], v[196:197]
	v_pk_mul_f32 v[236:237], v[12:13], v[12:13]
	v_pk_mul_f32 v[238:239], v[14:15], v[14:15]
	v_add_f32_e32 v229, v229, v236
	v_add_f32_e32 v229, v229, v237
	v_add_f32_e32 v229, v229, v238
	v_add_f32_e32 v229, v229, v239
	v_pk_mul_f32 v[236:237], v[8:9], v[230:231] op_sel_hi:[1,0]
	v_pk_mul_f32 v[238:239], v[10:11], v[230:231] op_sel_hi:[1,0]
	v_exp_f32_e32 v236, v236
	v_exp_f32_e32 v237, v237
	v_exp_f32_e32 v238, v238
	v_exp_f32_e32 v239, v239
	v_pk_add_f32 v[236:237], v[236:237], 1.0 op_sel_hi:[1,0]
	v_pk_add_f32 v[238:239], v[238:239], 1.0 op_sel_hi:[1,0]
	v_rcp_f32_e32 v236, v236
	v_rcp_f32_e32 v237, v237
	v_rcp_f32_e32 v238, v238
	v_rcp_f32_e32 v239, v239
	v_lshlrev_b32_e32 v232, 16, v222
	v_and_b32_e32 v233, 0xffff0000, v222
	v_lshlrev_b32_e32 v234, 16, v223
	v_and_b32_e32 v235, 0xffff0000, v223
	v_pk_fma_f32 v[8:9], v[236:237], v[232:233], v[198:199]
	v_pk_fma_f32 v[10:11], v[238:239], v[234:235], v[200:201]
	v_pk_mul_f32 v[236:237], v[8:9], v[8:9]
	v_pk_mul_f32 v[238:239], v[10:11], v[10:11]
	v_add_f32_e32 v229, v229, v236
	v_add_f32_e32 v229, v229, v237
	v_add_f32_e32 v229, v229, v238
	v_add_f32_e32 v229, v229, v239
	v_pk_mul_f32 v[236:237], v[4:5], v[230:231] op_sel_hi:[1,0]
	v_pk_mul_f32 v[238:239], v[6:7], v[230:231] op_sel_hi:[1,0]
	v_exp_f32_e32 v236, v236
	v_exp_f32_e32 v237, v237
	v_exp_f32_e32 v238, v238
	v_exp_f32_e32 v239, v239
	v_pk_add_f32 v[236:237], v[236:237], 1.0 op_sel_hi:[1,0]
	v_pk_add_f32 v[238:239], v[238:239], 1.0 op_sel_hi:[1,0]
	v_rcp_f32_e32 v236, v236
	v_rcp_f32_e32 v237, v237
	v_rcp_f32_e32 v238, v238
	v_rcp_f32_e32 v239, v239
	v_lshlrev_b32_e32 v232, 16, v244
	v_and_b32_e32 v233, 0xffff0000, v244
	v_lshlrev_b32_e32 v234, 16, v245
	v_and_b32_e32 v235, 0xffff0000, v245
	v_pk_fma_f32 v[4:5], v[236:237], v[232:233], v[202:203]
	v_pk_fma_f32 v[6:7], v[238:239], v[234:235], v[204:205]
	v_pk_mul_f32 v[236:237], v[4:5], v[4:5]
	v_pk_mul_f32 v[238:239], v[6:7], v[6:7]
	v_add_f32_e32 v229, v229, v236
	v_add_f32_e32 v229, v229, v237
	v_add_f32_e32 v229, v229, v238
	v_add_f32_e32 v229, v229, v239
	v_pk_mul_f32 v[236:237], v[0:1], v[230:231] op_sel_hi:[1,0]
	v_pk_mul_f32 v[238:239], v[2:3], v[230:231] op_sel_hi:[1,0]
	v_exp_f32_e32 v236, v236
	v_exp_f32_e32 v237, v237
	v_exp_f32_e32 v238, v238
	v_exp_f32_e32 v239, v239
	v_pk_add_f32 v[236:237], v[236:237], 1.0 op_sel_hi:[1,0]
	v_pk_add_f32 v[238:239], v[238:239], 1.0 op_sel_hi:[1,0]
	v_rcp_f32_e32 v236, v236
	v_rcp_f32_e32 v237, v237
	v_rcp_f32_e32 v238, v238
	v_rcp_f32_e32 v239, v239
	v_lshlrev_b32_e32 v232, 16, v246
	v_and_b32_e32 v233, 0xffff0000, v246
	v_lshlrev_b32_e32 v234, 16, v247
	v_and_b32_e32 v235, 0xffff0000, v247
	v_pk_fma_f32 v[0:1], v[236:237], v[232:233], v[206:207]
	v_pk_fma_f32 v[2:3], v[238:239], v[234:235], v[208:209]
	v_pk_mul_f32 v[236:237], v[0:1], v[0:1]
	v_pk_mul_f32 v[238:239], v[2:3], v[2:3]
	v_add_f32_e32 v229, v229, v236
	v_add_f32_e32 v229, v229, v237
	v_add_f32_e32 v229, v229, v238
	v_add_f32_e32 v229, v229, v239
	v_xor_b32_e32 v232, 64, v224
	ds_bpermute_b32 v233, v232, v229
	s_waitcnt lgkmcnt(0)
	v_add_f32_e32 v229, v229, v233
	v_xor_b32_e32 v232, 0x80, v224
	ds_bpermute_b32 v233, v232, v229
	s_waitcnt lgkmcnt(0)
	v_add_f32_e32 v229, v229, v233
	s_and_saveexec_b64 s[100:101], s[98:99]
	global_atomic_add_f32 v226, v229, s[16:17] offset:704
	s_mov_b64 exec, s[100:101]
	s_mov_b64 s[12:13], exec
	s_branch .LBB0_2611
